# P2 attention tile loop: weights as f32 products of sigmoids (e=2^z, q=1/(1+e), suffix products, w=e*P*2^c), carried mass stays in log2 units; 34 instead of 48 transcendentals per lane-tile; all f32, b
# baseline (speedup 1.0000x reference)
; template <bool DIAG>
; __device__ __forceinline__ void sb_tile(const bf16x8 (&kf)[4], const bf16x8 (&vf)[4], const bf16x8 (&qf)[4], f32x16& o0, f32x16& o1, float& c, int rel0, int hi) {
;     f32x16 s;
; #pragma unroll
;     for (int r = 0; r < 16; ++r) s[r] = 0.f;
; #pragma unroll
;     for (int d0 = 0; d0 < 4; ++d0) s = __builtin_amdgcn_mfma_f32_32x32x16_bf16(kf[d0], qf[d0], s, 0, 0, 0);
;     float L[16]; float tot = 0.f;
; #pragma unroll
;     for (int r = 15; r >= 0; --r) {
;         const float z = s[r];
;         const float sp = fmaxf(z, 0.f) + __builtin_amdgcn_logf(1.0f + __builtin_amdgcn_exp2f(-fabsf(z)));
;         if (DIAG) tot += (r < rel0) ? -sp : 0.f; else tot -= sp;
;         L[r] = tot;
;     }
;     const float tot_o = __shfl_xor(tot, 32);
;     const float add = c + (hi == 0 ? tot_o : 0.f);
;     float w[16];
; #pragma unroll
;     for (int r = 0; r < 16; ++r) {
;         const float e = __builtin_amdgcn_exp2f(s[r] + L[r] + add);
;         w[r] = DIAG ? ((r < rel0) ? e : 0.f) : e;
;     }
;     c += tot + tot_o;
;     u32x4 p0, p1;
;     p0.x = cvt_pk_bf16(w[0], w[1]); p0.y = cvt_pk_bf16(w[2], w[3]); p0.z = cvt_pk_bf16(w[4], w[5]); p0.w = cvt_pk_bf16(w[6], w[7]);
;     p1.x = cvt_pk_bf16(w[8], w[9]); p1.y = cvt_pk_bf16(w[10], w[11]); p1.z = cvt_pk_bf16(w[12], w[13]); p1.w = cvt_pk_bf16(w[14], w[15]);
;     const bf16x8 pf0 = __builtin_bit_cast(bf16x8, p0), pf1 = __builtin_bit_cast(bf16x8, p1);
;     o0 = __builtin_amdgcn_mfma_f32_32x32x16_bf16(vf[0], pf0, o0, 0, 0, 0);
;     o0 = __builtin_amdgcn_mfma_f32_32x32x16_bf16(vf[1], pf1, o0, 0, 0, 0);
;     o1 = __builtin_amdgcn_mfma_f32_32x32x16_bf16(vf[2], pf0, o1, 0, 0, 0);
;     o1 = __builtin_amdgcn_mfma_f32_32x32x16_bf16(vf[3], pf1, o1, 0, 0, 0);
; }
; __device__ __forceinline__ void sb_attn_unit(const bf16_t* __restrict__ Q, const bf16_t* __restrict__ Kb, const bf16_t* __restrict__ VT, bf16_t* __restrict__ MIX, int b, int h, int qb, int lane) {
;     ...
;     for (int kv0 = q0 - 32; kv0 >= 0; kv0 -= 32) {
; #pragma unroll
;         for (int i = 0; i < 4; ++i) { kf[i] = kn[i]; vf[i] = vn[i]; }
;         kvn = kv0 >= 32 ? kv0 - 32 : 0;
; #pragma unroll
;         for (int i = 0; i < 4; ++i) { kn[i] = *(const bf16x8*)(kp + (size_t)kvn * 64 + 512 * i); vn[i] = *(const bf16x8*)(vp + (size_t)kvn * 64 + 512 * i); }
;         sb_tile<false>(kf, vf, qf, o0, o1, c, 0, hi);
.LBB0_354:
	s_ashr_i32 s55, s54, 31
	s_lshl_b64 s[54:55], s[54:55], 7
	v_lshl_add_u64 v[72:73], v[86:87], 0, s[54:55]
	global_load_dwordx4 v[32:35], v[72:73], off
	global_load_dwordx4 v[64:67], v[72:73], off offset:1024
	global_load_dwordx4 v[68:71], v[72:73], off offset:2048
	global_load_dwordx4 v[94:97], v[72:73], off offset:3072
	v_lshl_add_u64 v[92:93], v[88:89], 0, s[54:55]
	s_sub_i32 s53, s50, 32
	s_cmp_lg_u32 s50, 0
	s_cselect_b32 s54, s53, 0
	s_mov_b32 s50, s53
	s_waitcnt vmcnt(3)
	v_mfma_f32_32x32x16_bf16 v[32:47], v[32:35], v[48:51], 0
	s_waitcnt vmcnt(2)
	v_mfma_f32_32x32x16_bf16 v[32:47], v[64:67], v[52:55], v[32:47]
	s_waitcnt vmcnt(1)
	v_mfma_f32_32x32x16_bf16 v[32:47], v[68:71], v[56:59], v[32:47]
	global_load_dwordx4 v[72:75], v[92:93], off
	global_load_dwordx4 v[68:71], v[92:93], off offset:1024
	global_load_dwordx4 v[64:67], v[92:93], off offset:2048
	s_waitcnt vmcnt(3)
	v_mfma_f32_32x32x16_bf16 v[32:47], v[94:97], v[60:63], v[32:47]
	global_load_dwordx4 v[116:119], v[92:93], off offset:3072
	s_nop 10
	v_exp_f32_e32 v47, v47
	v_exp_f32_e32 v46, v46
	v_exp_f32_e32 v45, v45
	v_exp_f32_e32 v44, v44
	v_exp_f32_e32 v43, v43
	v_exp_f32_e32 v42, v42
	v_exp_f32_e32 v41, v41
	v_exp_f32_e32 v40, v40
	v_exp_f32_e32 v39, v39
	v_exp_f32_e32 v38, v38
	v_exp_f32_e32 v37, v37
	v_exp_f32_e32 v36, v36
	v_exp_f32_e32 v35, v35
	v_exp_f32_e32 v34, v34
	v_exp_f32_e32 v33, v33
	v_exp_f32_e32 v32, v32
	v_exp_f32_e32 v114, v90
	v_add_f32_e32 v113, 1.0, v47
	v_add_f32_e32 v112, 1.0, v46
	v_add_f32_e32 v111, 1.0, v45
	v_add_f32_e32 v110, 1.0, v44
	v_add_f32_e32 v109, 1.0, v43
	v_add_f32_e32 v108, 1.0, v42
	v_add_f32_e32 v107, 1.0, v41
	v_add_f32_e32 v106, 1.0, v40
	v_add_f32_e32 v105, 1.0, v39
	v_add_f32_e32 v104, 1.0, v38
	v_add_f32_e32 v103, 1.0, v37
	v_add_f32_e32 v102, 1.0, v36
	v_add_f32_e32 v101, 1.0, v35
	v_add_f32_e32 v100, 1.0, v34
	v_add_f32_e32 v99, 1.0, v33
	v_add_f32_e32 v98, 1.0, v32
	v_rcp_f32_e32 v113, v113
	v_rcp_f32_e32 v112, v112
	v_rcp_f32_e32 v111, v111
	v_rcp_f32_e32 v110, v110
	v_rcp_f32_e32 v109, v109
	v_rcp_f32_e32 v108, v108
	v_rcp_f32_e32 v107, v107
	v_rcp_f32_e32 v106, v106
	v_rcp_f32_e32 v105, v105
	v_rcp_f32_e32 v104, v104
	v_rcp_f32_e32 v103, v103
	v_rcp_f32_e32 v102, v102
	v_rcp_f32_e32 v101, v101
	v_rcp_f32_e32 v100, v100
	v_rcp_f32_e32 v99, v99
	v_rcp_f32_e32 v98, v98
	v_mul_f32_e32 v112, v112, v113
	v_mul_f32_e32 v111, v111, v112
	v_mul_f32_e32 v110, v110, v111
	v_mul_f32_e32 v109, v109, v110
	v_mul_f32_e32 v108, v108, v109
	v_mul_f32_e32 v107, v107, v108
	v_mul_f32_e32 v106, v106, v107
	v_mul_f32_e32 v105, v105, v106
	v_mul_f32_e32 v104, v104, v105
	v_mul_f32_e32 v103, v103, v104
	v_mul_f32_e32 v102, v102, v103
	v_mul_f32_e32 v101, v101, v102
	v_mul_f32_e32 v100, v100, v101
	v_mul_f32_e32 v99, v99, v100
	v_mul_f32_e32 v98, v98, v99
	ds_bpermute_b32 v115, v77, v98
	v_mul_f32_e32 v47, v47, v113
	v_mul_f32_e32 v46, v46, v112
	v_mul_f32_e32 v45, v45, v111
	v_mul_f32_e32 v44, v44, v110
	v_mul_f32_e32 v43, v43, v109
	v_mul_f32_e32 v42, v42, v108
	v_mul_f32_e32 v41, v41, v107
	v_mul_f32_e32 v40, v40, v106
	v_mul_f32_e32 v39, v39, v105
	v_mul_f32_e32 v38, v38, v104
	v_mul_f32_e32 v37, v37, v103
	v_mul_f32_e32 v36, v36, v102
	v_mul_f32_e32 v35, v35, v101
	v_mul_f32_e32 v34, v34, v100
	v_mul_f32_e32 v33, v33, v99
	v_mul_f32_e32 v32, v32, v98
	s_waitcnt lgkmcnt(0)
	v_cndmask_b32_e64 v120, 1.0, v115, s[40:41]
	v_mul_f32_e32 v114, v114, v120
	v_mul_f32_e32 v32, v32, v114
	v_mul_f32_e32 v33, v33, v114
	v_mul_f32_e32 v34, v34, v114
	v_mul_f32_e32 v35, v35, v114
	v_mul_f32_e32 v36, v36, v114
	v_mul_f32_e32 v37, v37, v114
	v_mul_f32_e32 v38, v38, v114
	v_mul_f32_e32 v39, v39, v114
	v_mul_f32_e32 v40, v40, v114
	v_mul_f32_e32 v41, v41, v114
	v_mul_f32_e32 v42, v42, v114
	v_mul_f32_e32 v43, v43, v114
	v_mul_f32_e32 v44, v44, v114
	v_mul_f32_e32 v45, v45, v114
	v_mul_f32_e32 v46, v46, v114
	v_mul_f32_e32 v47, v47, v114
	v_cvt_pk_bf16_f32 v32, v32, v33
	v_cvt_pk_bf16_f32 v33, v34, v35
	v_cvt_pk_bf16_f32 v34, v36, v37
	v_cvt_pk_bf16_f32 v35, v38, v39
	v_cvt_pk_bf16_f32 v36, v40, v41
	v_cvt_pk_bf16_f32 v37, v42, v43
	v_cvt_pk_bf16_f32 v38, v44, v45
	v_cvt_pk_bf16_f32 v39, v46, v47
	s_waitcnt vmcnt(0)
	v_mfma_f32_32x32x16_bf16 v[0:15], v[72:75], v[32:35], v[0:15]
	v_mfma_f32_32x32x16_bf16 v[16:31], v[64:67], v[32:35], v[16:31]
	v_mul_f32_e32 v120, v98, v115
	v_log_f32_e32 v120, v120
	v_mfma_f32_32x32x16_bf16 v[0:15], v[68:71], v[36:39], v[0:15]
	v_mfma_f32_32x32x16_bf16 v[16:31], v[116:119], v[36:39], v[16:31]
	v_add_f32_e32 v90, v90, v120
	v_cmp_gt_f32_e32 vcc, s59, v90
	s_cmp_eq_u64 vcc, exec
	s_cselect_b64 s[56:57], -1, 0
	s_andn2_b64 vcc, exec, s[56:57]
	s_cbranch_vccz .LBB0_352
